# x-projection GEMM main loop: 4/4/4/4 LDS-DMA loads per load segment (the fourth segment's two B pieces issued at the head of the next iteration, pointer from the running B pointer, no re-derivation)
# speedup vs baseline: 1.0114x; 1.0016x over previous
.LBB0_630:
	s_ashr_i32 s85, s84, 31
	s_lshl_b64 s[22:23], s[84:85], 20
	s_cmp_eq_u32 s52, 0
	v_mov_b64_e32 v[0:1], 0x3a0
	s_cselect_b32 s31, s14, s50
	v_cmp_lt_i64_e32 vcc, s[76:77], v[0:1]
	s_cselect_b32 s30, s15, s51
	s_cselect_b32 s38, s8, s14
	s_cselect_b32 s39, s9, s15
	s_add_u32 s76, s31, s22
	s_addc_u32 s77, s30, s23
	s_and_b64 s[22:23], vcc, exec
	s_cselect_b32 s30, s77, s89
	s_cselect_b32 s31, s76, s88
	s_ashr_i32 s83, s82, 31
	s_lshl_b64 s[22:23], s[82:83], 20
	s_add_u32 s86, s38, s22
	s_addc_u32 s87, s39, s23
	s_and_b64 s[22:23], vcc, exec
	s_cselect_b32 s38, s87, s91
	s_cselect_b32 s39, s86, s90
	s_add_u32 s88, s88, 0x80080
	s_addc_u32 s89, s89, 0
	s_add_u32 s41, s90, 0x100
	s_addc_u32 s42, s91, 0
	s_mov_b32 s43, -2
	s_add_u32 s22, s88, 0xfff80080
	s_addc_u32 s23, s89, -1
	s_add_u32 s44, s88, 0xfff80000
	s_addc_u32 s45, s89, -1
	s_cmp_eq_u32 s43, 28
	s_cselect_b32 s23, s30, s23
	s_cselect_b32 s22, s31, s22
	s_cselect_b32 s91, s38, s42
	s_cselect_b32 s90, s39, s41
	s_add_i32 s81, 0, 0x14000
	ds_read_b128 v[144:147], v222
	ds_read_b128 v[148:151], v222 offset:1024
	ds_read_b128 v[152:155], v222 offset:2048
	ds_read_b128 v[156:159], v222 offset:3072
	ds_read_b128 v[160:163], v223
	ds_read_b128 v[164:167], v223 offset:1024
	ds_read_b128 v[168:171], v223 offset:2048
	ds_read_b128 v[172:175], v223 offset:3072
	s_mov_b32 m0, s92
	ds_read_b128 v[176:179], v143
	ds_read_b128 v[180:183], v143 offset:1024
	ds_read_b128 v[184:187], v143 offset:2048
	ds_read_b128 v[188:191], v143 offset:3072
	ds_read_b128 v[192:195], v143 offset:4096
	ds_read_b128 v[196:199], v143 offset:5120
	ds_read_b128 v[200:203], v143 offset:6144
	ds_read_b128 v[204:207], v143 offset:7168
	global_load_lds_dwordx4 v128, s[44:45]
	s_mov_b32 m0, s6
	s_nop 0
	global_load_lds_dwordx4 v132, s[44:45]
	s_add_i32 m0, s57, 0xc000
	s_nop 0
	global_load_lds_dwordx4 v136, s[88:89]
	s_add_i32 m0, s57, 0xe000
	s_nop 0
	global_load_lds_dwordx4 v138, s[88:89]
	s_waitcnt vmcnt(8)
	s_waitcnt lgkmcnt(0)
	s_barrier
	v_mfma_f32_16x16x32_bf16 v[124:127], v[144:147], v[176:179], 0
	v_mfma_f32_16x16x32_bf16 v[120:123], v[152:155], v[176:179], 0
	v_mfma_f32_16x16x32_bf16 v[116:119], v[144:147], v[184:187], 0
	v_mfma_f32_16x16x32_bf16 v[112:115], v[152:155], v[184:187], 0
	v_mfma_f32_16x16x32_bf16 v[100:103], v[144:147], v[192:195], 0
	v_mfma_f32_16x16x32_bf16 v[96:99], v[152:155], v[192:195], 0
	v_mfma_f32_16x16x32_bf16 v[84:87], v[144:147], v[200:203], 0
	v_mfma_f32_16x16x32_bf16 v[80:83], v[152:155], v[200:203], 0
	v_mfma_f32_16x16x32_bf16 v[124:127], v[148:151], v[180:183], v[124:127]
	v_mfma_f32_16x16x32_bf16 v[120:123], v[156:159], v[180:183], v[120:123]
	v_mfma_f32_16x16x32_bf16 v[116:119], v[148:151], v[188:191], v[116:119]
	v_mfma_f32_16x16x32_bf16 v[112:115], v[156:159], v[188:191], v[112:115]
	v_mfma_f32_16x16x32_bf16 v[100:103], v[148:151], v[196:199], v[100:103]
	v_mfma_f32_16x16x32_bf16 v[96:99], v[156:159], v[196:199], v[96:99]
	v_mfma_f32_16x16x32_bf16 v[84:87], v[148:151], v[204:207], v[84:87]
	v_mfma_f32_16x16x32_bf16 v[80:83], v[156:159], v[204:207], v[80:83]
	v_mfma_f32_16x16x32_bf16 v[108:111], v[160:163], v[176:179], 0
	v_mfma_f32_16x16x32_bf16 v[104:107], v[168:171], v[176:179], 0
	v_mfma_f32_16x16x32_bf16 v[92:95], v[160:163], v[184:187], 0
	v_mfma_f32_16x16x32_bf16 v[88:91], v[168:171], v[184:187], 0
	v_mfma_f32_16x16x32_bf16 v[76:79], v[160:163], v[192:195], 0
	v_mfma_f32_16x16x32_bf16 v[72:75], v[168:171], v[192:195], 0
	v_mfma_f32_16x16x32_bf16 v[68:71], v[160:163], v[200:203], 0
	v_mfma_f32_16x16x32_bf16 v[64:67], v[168:171], v[200:203], 0
	v_mfma_f32_16x16x32_bf16 v[108:111], v[164:167], v[180:183], v[108:111]
	v_mfma_f32_16x16x32_bf16 v[104:107], v[172:175], v[180:183], v[104:107]
	v_mfma_f32_16x16x32_bf16 v[92:95], v[164:167], v[188:191], v[92:95]
	v_mfma_f32_16x16x32_bf16 v[88:91], v[172:175], v[188:191], v[88:91]
	v_mfma_f32_16x16x32_bf16 v[76:79], v[164:167], v[196:199], v[76:79]
	v_mfma_f32_16x16x32_bf16 v[72:75], v[172:175], v[196:199], v[72:75]
	v_mfma_f32_16x16x32_bf16 v[68:71], v[164:167], v[204:207], v[68:71]
	v_mfma_f32_16x16x32_bf16 v[64:67], v[172:175], v[204:207], v[64:67]
	s_barrier
	s_add_i32 s44, s96, 0x10000
	s_mov_b32 m0, s44
	ds_read_b128 v[176:179], v143 offset:16384
	ds_read_b128 v[180:183], v143 offset:17408
	ds_read_b128 v[184:187], v143 offset:18432
	ds_read_b128 v[188:191], v143 offset:19456
	ds_read_b128 v[192:195], v143 offset:20480
	ds_read_b128 v[196:199], v143 offset:21504
	ds_read_b128 v[200:203], v143 offset:22528
	ds_read_b128 v[204:207], v143 offset:23552
	global_load_lds_dwordx4 v130, s[90:91]
	s_add_i32 m0, s44, 0x2000
	s_add_u32 s44, s90, 0x80000
	s_addc_u32 s45, s91, 0
	s_add_i32 s81, s81, s96
	global_load_lds_dwordx4 v134, s[90:91]
	s_mov_b32 m0, s81
	s_nop 0
	global_load_lds_dwordx4 v130, s[44:45]
	s_add_i32 m0, s81, 0x2000
	s_nop 0
	global_load_lds_dwordx4 v134, s[44:45]
	s_waitcnt vmcnt(6)
	s_waitcnt lgkmcnt(0)
	s_barrier
	v_mfma_f32_16x16x32_bf16 v[60:63], v[144:147], v[176:179], 0
	v_mfma_f32_16x16x32_bf16 v[56:59], v[152:155], v[176:179], 0
	v_mfma_f32_16x16x32_bf16 v[52:55], v[144:147], v[184:187], 0
	v_mfma_f32_16x16x32_bf16 v[48:51], v[152:155], v[184:187], 0
	v_mfma_f32_16x16x32_bf16 v[36:39], v[144:147], v[192:195], 0
	v_mfma_f32_16x16x32_bf16 v[32:35], v[152:155], v[192:195], 0
	v_mfma_f32_16x16x32_bf16 v[20:23], v[144:147], v[200:203], 0
	v_mfma_f32_16x16x32_bf16 v[16:19], v[152:155], v[200:203], 0
	v_mfma_f32_16x16x32_bf16 v[60:63], v[148:151], v[180:183], v[60:63]
	v_mfma_f32_16x16x32_bf16 v[56:59], v[156:159], v[180:183], v[56:59]
	v_mfma_f32_16x16x32_bf16 v[52:55], v[148:151], v[188:191], v[52:55]
	v_mfma_f32_16x16x32_bf16 v[48:51], v[156:159], v[188:191], v[48:51]
	v_mfma_f32_16x16x32_bf16 v[36:39], v[148:151], v[196:199], v[36:39]
	v_mfma_f32_16x16x32_bf16 v[32:35], v[156:159], v[196:199], v[32:35]
	v_mfma_f32_16x16x32_bf16 v[20:23], v[148:151], v[204:207], v[20:23]
	v_mfma_f32_16x16x32_bf16 v[16:19], v[156:159], v[204:207], v[16:19]
	v_mfma_f32_16x16x32_bf16 v[44:47], v[160:163], v[176:179], 0
	v_mfma_f32_16x16x32_bf16 v[40:43], v[168:171], v[176:179], 0
	v_mfma_f32_16x16x32_bf16 v[28:31], v[160:163], v[184:187], 0
	v_mfma_f32_16x16x32_bf16 v[24:27], v[168:171], v[184:187], 0
	v_mfma_f32_16x16x32_bf16 v[12:15], v[160:163], v[192:195], 0
	v_mfma_f32_16x16x32_bf16 v[8:11], v[168:171], v[192:195], 0
	v_mfma_f32_16x16x32_bf16 v[4:7], v[160:163], v[200:203], 0
	v_mfma_f32_16x16x32_bf16 v[0:3], v[168:171], v[200:203], 0
	v_mfma_f32_16x16x32_bf16 v[44:47], v[164:167], v[180:183], v[44:47]
	v_mfma_f32_16x16x32_bf16 v[40:43], v[172:175], v[180:183], v[40:43]
	v_mfma_f32_16x16x32_bf16 v[28:31], v[164:167], v[188:191], v[28:31]
	v_mfma_f32_16x16x32_bf16 v[24:27], v[172:175], v[188:191], v[24:27]
	v_mfma_f32_16x16x32_bf16 v[12:15], v[164:167], v[196:199], v[12:15]
	v_mfma_f32_16x16x32_bf16 v[8:11], v[172:175], v[196:199], v[8:11]
	v_mfma_f32_16x16x32_bf16 v[4:7], v[164:167], v[204:207], v[4:7]
	v_mfma_f32_16x16x32_bf16 v[0:3], v[172:175], v[204:207], v[0:3]
	s_barrier
	s_add_i32 s44, 0, 0x18000
	s_add_i32 s45, 0, 0x1c000
	ds_read_b128 v[144:147], v224
	ds_read_b128 v[148:151], v224 offset:1024
	ds_read_b128 v[152:155], v224 offset:2048
	ds_read_b128 v[156:159], v224 offset:3072
	ds_read_b128 v[160:163], v225
	ds_read_b128 v[164:167], v225 offset:1024
	ds_read_b128 v[168:171], v225 offset:2048
	ds_read_b128 v[172:175], v225 offset:3072
	ds_read_b128 v[176:179], v143 offset:32768
	ds_read_b128 v[180:183], v143 offset:33792
	ds_read_b128 v[184:187], v143 offset:34816
	ds_read_b128 v[188:191], v143 offset:35840
	ds_read_b128 v[192:195], v143 offset:36864
	ds_read_b128 v[196:199], v143 offset:37888
	ds_read_b128 v[200:203], v143 offset:38912
	ds_read_b128 v[204:207], v143 offset:39936
	s_mov_b32 m0, s57
	s_nop 0
	global_load_lds_dwordx4 v128, s[22:23]
	s_mov_b32 m0, s97
	s_nop 0
	global_load_lds_dwordx4 v132, s[22:23]
	s_mov_b32 m0, s93
	s_add_u32 s22, s22, 0x80000
	s_addc_u32 s23, s23, 0
	global_load_lds_dwordx4 v128, s[22:23]
	s_mov_b32 m0, s94
	s_nop 0
	global_load_lds_dwordx4 v132, s[22:23]
	s_waitcnt vmcnt(8)
	s_waitcnt lgkmcnt(0)
	s_barrier
	v_mfma_f32_16x16x32_bf16 v[124:127], v[144:147], v[176:179], v[124:127]
	v_mfma_f32_16x16x32_bf16 v[120:123], v[152:155], v[176:179], v[120:123]
	v_mfma_f32_16x16x32_bf16 v[116:119], v[144:147], v[184:187], v[116:119]
	v_mfma_f32_16x16x32_bf16 v[112:115], v[152:155], v[184:187], v[112:115]
	v_mfma_f32_16x16x32_bf16 v[100:103], v[144:147], v[192:195], v[100:103]
	v_mfma_f32_16x16x32_bf16 v[96:99], v[152:155], v[192:195], v[96:99]
	v_mfma_f32_16x16x32_bf16 v[84:87], v[144:147], v[200:203], v[84:87]
	v_mfma_f32_16x16x32_bf16 v[80:83], v[152:155], v[200:203], v[80:83]
	v_mfma_f32_16x16x32_bf16 v[124:127], v[148:151], v[180:183], v[124:127]
	v_mfma_f32_16x16x32_bf16 v[120:123], v[156:159], v[180:183], v[120:123]
	v_mfma_f32_16x16x32_bf16 v[116:119], v[148:151], v[188:191], v[116:119]
	v_mfma_f32_16x16x32_bf16 v[112:115], v[156:159], v[188:191], v[112:115]
	v_mfma_f32_16x16x32_bf16 v[100:103], v[148:151], v[196:199], v[100:103]
	v_mfma_f32_16x16x32_bf16 v[96:99], v[156:159], v[196:199], v[96:99]
	v_mfma_f32_16x16x32_bf16 v[84:87], v[148:151], v[204:207], v[84:87]
	v_mfma_f32_16x16x32_bf16 v[80:83], v[156:159], v[204:207], v[80:83]
	v_mfma_f32_16x16x32_bf16 v[108:111], v[160:163], v[176:179], v[108:111]
	v_mfma_f32_16x16x32_bf16 v[104:107], v[168:171], v[176:179], v[104:107]
	v_mfma_f32_16x16x32_bf16 v[92:95], v[160:163], v[184:187], v[92:95]
	v_mfma_f32_16x16x32_bf16 v[88:91], v[168:171], v[184:187], v[88:91]
	v_mfma_f32_16x16x32_bf16 v[76:79], v[160:163], v[192:195], v[76:79]
	v_mfma_f32_16x16x32_bf16 v[72:75], v[168:171], v[192:195], v[72:75]
	v_mfma_f32_16x16x32_bf16 v[68:71], v[160:163], v[200:203], v[68:71]
	v_mfma_f32_16x16x32_bf16 v[64:67], v[168:171], v[200:203], v[64:67]
	v_mfma_f32_16x16x32_bf16 v[108:111], v[164:167], v[180:183], v[108:111]
	v_mfma_f32_16x16x32_bf16 v[104:107], v[172:175], v[180:183], v[104:107]
	v_mfma_f32_16x16x32_bf16 v[92:95], v[164:167], v[188:191], v[92:95]
	v_mfma_f32_16x16x32_bf16 v[88:91], v[172:175], v[188:191], v[88:91]
	v_mfma_f32_16x16x32_bf16 v[76:79], v[164:167], v[196:199], v[76:79]
	v_mfma_f32_16x16x32_bf16 v[72:75], v[172:175], v[196:199], v[72:75]
	v_mfma_f32_16x16x32_bf16 v[68:71], v[164:167], v[204:207], v[68:71]
	v_mfma_f32_16x16x32_bf16 v[64:67], v[172:175], v[204:207], v[64:67]
	s_barrier
	s_add_i32 s22, s44, s96
	s_add_i32 m0, s22, 0xffffff80
	ds_read_b128 v[176:179], v143 offset:49152
	ds_read_b128 v[180:183], v143 offset:50176
	ds_read_b128 v[184:187], v143 offset:51200
	ds_read_b128 v[188:191], v143 offset:52224
	ds_read_b128 v[192:195], v143 offset:53248
	ds_read_b128 v[196:199], v143 offset:54272
	ds_read_b128 v[200:203], v143 offset:55296
	ds_read_b128 v[204:207], v143 offset:56320
	global_load_lds_dwordx4 v130, s[90:91] offset:128
	s_add_i32 m0, s22, 0x1f80
	s_add_u32 s22, s90, 0x80080
	s_addc_u32 s23, s91, 0
	s_add_i32 s44, s45, s96
	global_load_lds_dwordx4 v134, s[90:91] offset:128
	s_mov_b32 m0, s44
	s_nop 0
	global_load_lds_dwordx4 v130, s[22:23]
	s_add_i32 m0, s44, 0x2000
	s_nop 0
	global_load_lds_dwordx4 v134, s[22:23]
	s_waitcnt vmcnt(6)
	s_waitcnt lgkmcnt(0)
	s_barrier
	v_mfma_f32_16x16x32_bf16 v[60:63], v[144:147], v[176:179], v[60:63]
	v_mfma_f32_16x16x32_bf16 v[56:59], v[152:155], v[176:179], v[56:59]
	v_mfma_f32_16x16x32_bf16 v[52:55], v[144:147], v[184:187], v[52:55]
	v_mfma_f32_16x16x32_bf16 v[48:51], v[152:155], v[184:187], v[48:51]
	v_mfma_f32_16x16x32_bf16 v[36:39], v[144:147], v[192:195], v[36:39]
	v_mfma_f32_16x16x32_bf16 v[32:35], v[152:155], v[192:195], v[32:35]
	v_mfma_f32_16x16x32_bf16 v[20:23], v[144:147], v[200:203], v[20:23]
	v_mfma_f32_16x16x32_bf16 v[16:19], v[152:155], v[200:203], v[16:19]
	v_mfma_f32_16x16x32_bf16 v[60:63], v[148:151], v[180:183], v[60:63]
	v_mfma_f32_16x16x32_bf16 v[56:59], v[156:159], v[180:183], v[56:59]
	v_mfma_f32_16x16x32_bf16 v[52:55], v[148:151], v[188:191], v[52:55]
	v_mfma_f32_16x16x32_bf16 v[48:51], v[156:159], v[188:191], v[48:51]
	v_mfma_f32_16x16x32_bf16 v[36:39], v[148:151], v[196:199], v[36:39]
	v_mfma_f32_16x16x32_bf16 v[32:35], v[156:159], v[196:199], v[32:35]
	v_mfma_f32_16x16x32_bf16 v[20:23], v[148:151], v[204:207], v[20:23]
	v_mfma_f32_16x16x32_bf16 v[16:19], v[156:159], v[204:207], v[16:19]
	v_mfma_f32_16x16x32_bf16 v[44:47], v[160:163], v[176:179], v[44:47]
	v_mfma_f32_16x16x32_bf16 v[40:43], v[168:171], v[176:179], v[40:43]
	v_mfma_f32_16x16x32_bf16 v[28:31], v[160:163], v[184:187], v[28:31]
	v_mfma_f32_16x16x32_bf16 v[24:27], v[168:171], v[184:187], v[24:27]
	v_mfma_f32_16x16x32_bf16 v[12:15], v[160:163], v[192:195], v[12:15]
	v_mfma_f32_16x16x32_bf16 v[8:11], v[168:171], v[192:195], v[8:11]
	v_mfma_f32_16x16x32_bf16 v[4:7], v[160:163], v[200:203], v[4:7]
	v_mfma_f32_16x16x32_bf16 v[0:3], v[168:171], v[200:203], v[0:3]
	v_mfma_f32_16x16x32_bf16 v[44:47], v[164:167], v[180:183], v[44:47]
	v_mfma_f32_16x16x32_bf16 v[40:43], v[172:175], v[180:183], v[40:43]
	v_mfma_f32_16x16x32_bf16 v[28:31], v[164:167], v[188:191], v[28:31]
	v_mfma_f32_16x16x32_bf16 v[24:27], v[172:175], v[188:191], v[24:27]
	v_mfma_f32_16x16x32_bf16 v[12:15], v[164:167], v[196:199], v[12:15]
	v_mfma_f32_16x16x32_bf16 v[8:11], v[172:175], v[196:199], v[8:11]
	v_mfma_f32_16x16x32_bf16 v[4:7], v[164:167], v[204:207], v[4:7]
	v_mfma_f32_16x16x32_bf16 v[0:3], v[172:175], v[204:207], v[0:3]
	s_barrier
	s_add_i32 s43, s43, 2
	s_add_u32 s88, s88, 0x100
	s_addc_u32 s89, s89, 0
	s_add_u32 s41, s41, 0x100
	s_addc_u32 s42, s42, 0
	s_cmp_gt_u32 s43, 29
	s_cbranch_scc0 .LBB0_631
.LBB0_631:
	s_add_u32 s22, s88, 0xfff80080
	s_addc_u32 s23, s89, -1
	s_add_u32 s44, s88, 0xfff80000
	s_addc_u32 s45, s89, -1
	s_cmp_eq_u32 s43, 28
	s_cselect_b32 s23, s30, s23
	s_cselect_b32 s22, s31, s22
	s_cselect_b32 s91, s38, s42
	s_cselect_b32 s90, s39, s41
	s_add_i32 s81, 0, 0x14000
	ds_read_b128 v[144:147], v222
	ds_read_b128 v[148:151], v222 offset:1024
	ds_read_b128 v[152:155], v222 offset:2048
	ds_read_b128 v[156:159], v222 offset:3072
	ds_read_b128 v[160:163], v223
	ds_read_b128 v[164:167], v223 offset:1024
	ds_read_b128 v[168:171], v223 offset:2048
	ds_read_b128 v[172:175], v223 offset:3072
	s_mov_b32 m0, s92
	ds_read_b128 v[176:179], v143
	ds_read_b128 v[180:183], v143 offset:1024
	ds_read_b128 v[184:187], v143 offset:2048
	ds_read_b128 v[188:191], v143 offset:3072
	ds_read_b128 v[192:195], v143 offset:4096
	ds_read_b128 v[196:199], v143 offset:5120
	ds_read_b128 v[200:203], v143 offset:6144
	ds_read_b128 v[204:207], v143 offset:7168
	global_load_lds_dwordx4 v128, s[44:45]
	s_mov_b32 m0, s6
	s_nop 0
	global_load_lds_dwordx4 v132, s[44:45]
	s_add_i32 m0, s57, 0xc000
	s_nop 0
	global_load_lds_dwordx4 v136, s[88:89]
	s_add_i32 m0, s57, 0xe000
	s_nop 0
	global_load_lds_dwordx4 v138, s[88:89]
	s_waitcnt vmcnt(8)
	s_waitcnt lgkmcnt(0)
	s_barrier
	v_mfma_f32_16x16x32_bf16 v[124:127], v[144:147], v[176:179], v[124:127]
	v_mfma_f32_16x16x32_bf16 v[120:123], v[152:155], v[176:179], v[120:123]
	v_mfma_f32_16x16x32_bf16 v[116:119], v[144:147], v[184:187], v[116:119]
	v_mfma_f32_16x16x32_bf16 v[112:115], v[152:155], v[184:187], v[112:115]
	v_mfma_f32_16x16x32_bf16 v[100:103], v[144:147], v[192:195], v[100:103]
	v_mfma_f32_16x16x32_bf16 v[96:99], v[152:155], v[192:195], v[96:99]
	v_mfma_f32_16x16x32_bf16 v[84:87], v[144:147], v[200:203], v[84:87]
	v_mfma_f32_16x16x32_bf16 v[80:83], v[152:155], v[200:203], v[80:83]
	v_mfma_f32_16x16x32_bf16 v[124:127], v[148:151], v[180:183], v[124:127]
	v_mfma_f32_16x16x32_bf16 v[120:123], v[156:159], v[180:183], v[120:123]
	v_mfma_f32_16x16x32_bf16 v[116:119], v[148:151], v[188:191], v[116:119]
	v_mfma_f32_16x16x32_bf16 v[112:115], v[156:159], v[188:191], v[112:115]
	v_mfma_f32_16x16x32_bf16 v[100:103], v[148:151], v[196:199], v[100:103]
	v_mfma_f32_16x16x32_bf16 v[96:99], v[156:159], v[196:199], v[96:99]
	v_mfma_f32_16x16x32_bf16 v[84:87], v[148:151], v[204:207], v[84:87]
	v_mfma_f32_16x16x32_bf16 v[80:83], v[156:159], v[204:207], v[80:83]
	v_mfma_f32_16x16x32_bf16 v[108:111], v[160:163], v[176:179], v[108:111]
	v_mfma_f32_16x16x32_bf16 v[104:107], v[168:171], v[176:179], v[104:107]
	v_mfma_f32_16x16x32_bf16 v[92:95], v[160:163], v[184:187], v[92:95]
	v_mfma_f32_16x16x32_bf16 v[88:91], v[168:171], v[184:187], v[88:91]
	v_mfma_f32_16x16x32_bf16 v[76:79], v[160:163], v[192:195], v[76:79]
	v_mfma_f32_16x16x32_bf16 v[72:75], v[168:171], v[192:195], v[72:75]
	v_mfma_f32_16x16x32_bf16 v[68:71], v[160:163], v[200:203], v[68:71]
	v_mfma_f32_16x16x32_bf16 v[64:67], v[168:171], v[200:203], v[64:67]
	v_mfma_f32_16x16x32_bf16 v[108:111], v[164:167], v[180:183], v[108:111]
	v_mfma_f32_16x16x32_bf16 v[104:107], v[172:175], v[180:183], v[104:107]
	v_mfma_f32_16x16x32_bf16 v[92:95], v[164:167], v[188:191], v[92:95]
	v_mfma_f32_16x16x32_bf16 v[88:91], v[172:175], v[188:191], v[88:91]
	v_mfma_f32_16x16x32_bf16 v[76:79], v[164:167], v[196:199], v[76:79]
	v_mfma_f32_16x16x32_bf16 v[72:75], v[172:175], v[196:199], v[72:75]
	v_mfma_f32_16x16x32_bf16 v[68:71], v[164:167], v[204:207], v[68:71]
	v_mfma_f32_16x16x32_bf16 v[64:67], v[172:175], v[204:207], v[64:67]
	s_barrier
	s_add_i32 s44, s96, 0x10000
	s_mov_b32 m0, s44
	ds_read_b128 v[176:179], v143 offset:16384
	ds_read_b128 v[180:183], v143 offset:17408
	ds_read_b128 v[184:187], v143 offset:18432
	ds_read_b128 v[188:191], v143 offset:19456
	ds_read_b128 v[192:195], v143 offset:20480
	ds_read_b128 v[196:199], v143 offset:21504
	ds_read_b128 v[200:203], v143 offset:22528
	ds_read_b128 v[204:207], v143 offset:23552
	global_load_lds_dwordx4 v130, s[90:91]
	s_add_i32 m0, s44, 0x2000
	s_add_u32 s44, s90, 0x80000
	s_addc_u32 s45, s91, 0
	s_add_i32 s81, s81, s96
	global_load_lds_dwordx4 v134, s[90:91]
	s_mov_b32 m0, s81
	s_nop 0
	global_load_lds_dwordx4 v130, s[44:45]
	s_add_i32 m0, s81, 0x2000
	s_nop 0
	global_load_lds_dwordx4 v134, s[44:45]
	s_waitcnt vmcnt(6)
	s_waitcnt lgkmcnt(0)
	s_barrier
	v_mfma_f32_16x16x32_bf16 v[60:63], v[144:147], v[176:179], v[60:63]
	v_mfma_f32_16x16x32_bf16 v[56:59], v[152:155], v[176:179], v[56:59]
	v_mfma_f32_16x16x32_bf16 v[52:55], v[144:147], v[184:187], v[52:55]
	v_mfma_f32_16x16x32_bf16 v[48:51], v[152:155], v[184:187], v[48:51]
	v_mfma_f32_16x16x32_bf16 v[36:39], v[144:147], v[192:195], v[36:39]
	v_mfma_f32_16x16x32_bf16 v[32:35], v[152:155], v[192:195], v[32:35]
	v_mfma_f32_16x16x32_bf16 v[20:23], v[144:147], v[200:203], v[20:23]
	v_mfma_f32_16x16x32_bf16 v[16:19], v[152:155], v[200:203], v[16:19]
	v_mfma_f32_16x16x32_bf16 v[60:63], v[148:151], v[180:183], v[60:63]
	v_mfma_f32_16x16x32_bf16 v[56:59], v[156:159], v[180:183], v[56:59]
	v_mfma_f32_16x16x32_bf16 v[52:55], v[148:151], v[188:191], v[52:55]
	v_mfma_f32_16x16x32_bf16 v[48:51], v[156:159], v[188:191], v[48:51]
	v_mfma_f32_16x16x32_bf16 v[36:39], v[148:151], v[196:199], v[36:39]
	v_mfma_f32_16x16x32_bf16 v[32:35], v[156:159], v[196:199], v[32:35]
	v_mfma_f32_16x16x32_bf16 v[20:23], v[148:151], v[204:207], v[20:23]
	v_mfma_f32_16x16x32_bf16 v[16:19], v[156:159], v[204:207], v[16:19]
	v_mfma_f32_16x16x32_bf16 v[44:47], v[160:163], v[176:179], v[44:47]
	v_mfma_f32_16x16x32_bf16 v[40:43], v[168:171], v[176:179], v[40:43]
	v_mfma_f32_16x16x32_bf16 v[28:31], v[160:163], v[184:187], v[28:31]
	v_mfma_f32_16x16x32_bf16 v[24:27], v[168:171], v[184:187], v[24:27]
	v_mfma_f32_16x16x32_bf16 v[12:15], v[160:163], v[192:195], v[12:15]
	v_mfma_f32_16x16x32_bf16 v[8:11], v[168:171], v[192:195], v[8:11]
	v_mfma_f32_16x16x32_bf16 v[4:7], v[160:163], v[200:203], v[4:7]
	v_mfma_f32_16x16x32_bf16 v[0:3], v[168:171], v[200:203], v[0:3]
	v_mfma_f32_16x16x32_bf16 v[44:47], v[164:167], v[180:183], v[44:47]
	v_mfma_f32_16x16x32_bf16 v[40:43], v[172:175], v[180:183], v[40:43]
	v_mfma_f32_16x16x32_bf16 v[28:31], v[164:167], v[188:191], v[28:31]
	v_mfma_f32_16x16x32_bf16 v[24:27], v[172:175], v[188:191], v[24:27]
	v_mfma_f32_16x16x32_bf16 v[12:15], v[164:167], v[196:199], v[12:15]
	v_mfma_f32_16x16x32_bf16 v[8:11], v[172:175], v[196:199], v[8:11]
	v_mfma_f32_16x16x32_bf16 v[4:7], v[164:167], v[204:207], v[4:7]
	v_mfma_f32_16x16x32_bf16 v[0:3], v[172:175], v[204:207], v[0:3]
	s_barrier
	s_add_i32 s44, 0, 0x18000
	s_add_i32 s45, 0, 0x1c000
	ds_read_b128 v[144:147], v224
	ds_read_b128 v[148:151], v224 offset:1024
	ds_read_b128 v[152:155], v224 offset:2048
	ds_read_b128 v[156:159], v224 offset:3072
	ds_read_b128 v[160:163], v225
	ds_read_b128 v[164:167], v225 offset:1024
	ds_read_b128 v[168:171], v225 offset:2048
	ds_read_b128 v[172:175], v225 offset:3072
	ds_read_b128 v[176:179], v143 offset:32768
	ds_read_b128 v[180:183], v143 offset:33792
	ds_read_b128 v[184:187], v143 offset:34816
	ds_read_b128 v[188:191], v143 offset:35840
	ds_read_b128 v[192:195], v143 offset:36864
	ds_read_b128 v[196:199], v143 offset:37888
	ds_read_b128 v[200:203], v143 offset:38912
	ds_read_b128 v[204:207], v143 offset:39936
	s_mov_b32 m0, s57
	s_nop 0
	global_load_lds_dwordx4 v128, s[22:23]
	s_mov_b32 m0, s97
	s_nop 0
	global_load_lds_dwordx4 v132, s[22:23]
	s_mov_b32 m0, s93
	s_add_u32 s22, s22, 0x80000
	s_addc_u32 s23, s23, 0
	global_load_lds_dwordx4 v128, s[22:23]
	s_mov_b32 m0, s94
	s_nop 0
	global_load_lds_dwordx4 v132, s[22:23]
	s_waitcnt vmcnt(8)
	s_waitcnt lgkmcnt(0)
	s_barrier
	v_mfma_f32_16x16x32_bf16 v[124:127], v[144:147], v[176:179], v[124:127]
	v_mfma_f32_16x16x32_bf16 v[120:123], v[152:155], v[176:179], v[120:123]
	v_mfma_f32_16x16x32_bf16 v[116:119], v[144:147], v[184:187], v[116:119]
	v_mfma_f32_16x16x32_bf16 v[112:115], v[152:155], v[184:187], v[112:115]
	v_mfma_f32_16x16x32_bf16 v[100:103], v[144:147], v[192:195], v[100:103]
	v_mfma_f32_16x16x32_bf16 v[96:99], v[152:155], v[192:195], v[96:99]
	v_mfma_f32_16x16x32_bf16 v[84:87], v[144:147], v[200:203], v[84:87]
	v_mfma_f32_16x16x32_bf16 v[80:83], v[152:155], v[200:203], v[80:83]
	v_mfma_f32_16x16x32_bf16 v[124:127], v[148:151], v[180:183], v[124:127]
	v_mfma_f32_16x16x32_bf16 v[120:123], v[156:159], v[180:183], v[120:123]
	v_mfma_f32_16x16x32_bf16 v[116:119], v[148:151], v[188:191], v[116:119]
	v_mfma_f32_16x16x32_bf16 v[112:115], v[156:159], v[188:191], v[112:115]
	v_mfma_f32_16x16x32_bf16 v[100:103], v[148:151], v[196:199], v[100:103]
	v_mfma_f32_16x16x32_bf16 v[96:99], v[156:159], v[196:199], v[96:99]
	v_mfma_f32_16x16x32_bf16 v[84:87], v[148:151], v[204:207], v[84:87]
	v_mfma_f32_16x16x32_bf16 v[80:83], v[156:159], v[204:207], v[80:83]
	v_mfma_f32_16x16x32_bf16 v[108:111], v[160:163], v[176:179], v[108:111]
	v_mfma_f32_16x16x32_bf16 v[104:107], v[168:171], v[176:179], v[104:107]
	v_mfma_f32_16x16x32_bf16 v[92:95], v[160:163], v[184:187], v[92:95]
	v_mfma_f32_16x16x32_bf16 v[88:91], v[168:171], v[184:187], v[88:91]
	v_mfma_f32_16x16x32_bf16 v[76:79], v[160:163], v[192:195], v[76:79]
	v_mfma_f32_16x16x32_bf16 v[72:75], v[168:171], v[192:195], v[72:75]
	v_mfma_f32_16x16x32_bf16 v[68:71], v[160:163], v[200:203], v[68:71]
	v_mfma_f32_16x16x32_bf16 v[64:67], v[168:171], v[200:203], v[64:67]
	v_mfma_f32_16x16x32_bf16 v[108:111], v[164:167], v[180:183], v[108:111]
	v_mfma_f32_16x16x32_bf16 v[104:107], v[172:175], v[180:183], v[104:107]
	v_mfma_f32_16x16x32_bf16 v[92:95], v[164:167], v[188:191], v[92:95]
	v_mfma_f32_16x16x32_bf16 v[88:91], v[172:175], v[188:191], v[88:91]
	v_mfma_f32_16x16x32_bf16 v[76:79], v[164:167], v[196:199], v[76:79]
	v_mfma_f32_16x16x32_bf16 v[72:75], v[172:175], v[196:199], v[72:75]
	v_mfma_f32_16x16x32_bf16 v[68:71], v[164:167], v[204:207], v[68:71]
	v_mfma_f32_16x16x32_bf16 v[64:67], v[172:175], v[204:207], v[64:67]
	s_barrier
	s_add_i32 s22, s44, s96
	s_add_i32 m0, s22, 0xffffff80
	ds_read_b128 v[176:179], v143 offset:49152
	ds_read_b128 v[180:183], v143 offset:50176
	ds_read_b128 v[184:187], v143 offset:51200
	ds_read_b128 v[188:191], v143 offset:52224
	ds_read_b128 v[192:195], v143 offset:53248
	ds_read_b128 v[196:199], v143 offset:54272
	ds_read_b128 v[200:203], v143 offset:55296
	ds_read_b128 v[204:207], v143 offset:56320
	global_load_lds_dwordx4 v130, s[90:91] offset:128
	s_add_i32 m0, s22, 0x1f80
	s_add_u32 s22, s90, 0x80080
	s_addc_u32 s23, s91, 0
	s_add_i32 s44, s45, s96
	global_load_lds_dwordx4 v134, s[90:91] offset:128
	s_mov_b32 m0, s44
	s_nop 0
	global_load_lds_dwordx4 v130, s[22:23]
	s_add_i32 m0, s44, 0x2000
	s_nop 0
	global_load_lds_dwordx4 v134, s[22:23]
	s_waitcnt vmcnt(6)
	s_waitcnt lgkmcnt(0)
	s_barrier
	v_mfma_f32_16x16x32_bf16 v[60:63], v[144:147], v[176:179], v[60:63]
	v_mfma_f32_16x16x32_bf16 v[56:59], v[152:155], v[176:179], v[56:59]
	v_mfma_f32_16x16x32_bf16 v[52:55], v[144:147], v[184:187], v[52:55]
	v_mfma_f32_16x16x32_bf16 v[48:51], v[152:155], v[184:187], v[48:51]
	v_mfma_f32_16x16x32_bf16 v[36:39], v[144:147], v[192:195], v[36:39]
	v_mfma_f32_16x16x32_bf16 v[32:35], v[152:155], v[192:195], v[32:35]
	v_mfma_f32_16x16x32_bf16 v[20:23], v[144:147], v[200:203], v[20:23]
	v_mfma_f32_16x16x32_bf16 v[16:19], v[152:155], v[200:203], v[16:19]
	v_mfma_f32_16x16x32_bf16 v[60:63], v[148:151], v[180:183], v[60:63]
	v_mfma_f32_16x16x32_bf16 v[56:59], v[156:159], v[180:183], v[56:59]
	v_mfma_f32_16x16x32_bf16 v[52:55], v[148:151], v[188:191], v[52:55]
	v_mfma_f32_16x16x32_bf16 v[48:51], v[156:159], v[188:191], v[48:51]
	v_mfma_f32_16x16x32_bf16 v[36:39], v[148:151], v[196:199], v[36:39]
	v_mfma_f32_16x16x32_bf16 v[32:35], v[156:159], v[196:199], v[32:35]
	v_mfma_f32_16x16x32_bf16 v[20:23], v[148:151], v[204:207], v[20:23]
	v_mfma_f32_16x16x32_bf16 v[16:19], v[156:159], v[204:207], v[16:19]
	v_mfma_f32_16x16x32_bf16 v[44:47], v[160:163], v[176:179], v[44:47]
	v_mfma_f32_16x16x32_bf16 v[40:43], v[168:171], v[176:179], v[40:43]
	v_mfma_f32_16x16x32_bf16 v[28:31], v[160:163], v[184:187], v[28:31]
	v_mfma_f32_16x16x32_bf16 v[24:27], v[168:171], v[184:187], v[24:27]
	v_mfma_f32_16x16x32_bf16 v[12:15], v[160:163], v[192:195], v[12:15]
	v_mfma_f32_16x16x32_bf16 v[8:11], v[168:171], v[192:195], v[8:11]
	v_mfma_f32_16x16x32_bf16 v[4:7], v[160:163], v[200:203], v[4:7]
	v_mfma_f32_16x16x32_bf16 v[0:3], v[168:171], v[200:203], v[0:3]
	v_mfma_f32_16x16x32_bf16 v[44:47], v[164:167], v[180:183], v[44:47]
	v_mfma_f32_16x16x32_bf16 v[40:43], v[172:175], v[180:183], v[40:43]
	v_mfma_f32_16x16x32_bf16 v[28:31], v[164:167], v[188:191], v[28:31]
	v_mfma_f32_16x16x32_bf16 v[24:27], v[172:175], v[188:191], v[24:27]
	v_mfma_f32_16x16x32_bf16 v[12:15], v[164:167], v[196:199], v[12:15]
	v_mfma_f32_16x16x32_bf16 v[8:11], v[172:175], v[196:199], v[8:11]
	v_mfma_f32_16x16x32_bf16 v[4:7], v[164:167], v[204:207], v[4:7]
	v_mfma_f32_16x16x32_bf16 v[0:3], v[172:175], v[204:207], v[0:3]
	s_barrier
	s_add_i32 s43, s43, 2
	s_add_u32 s88, s88, 0x100
	s_addc_u32 s89, s89, 0
	s_add_u32 s41, s41, 0x100
	s_addc_u32 s42, s42, 0
	s_cmp_gt_u32 s43, 29
	s_cbranch_scc0 .LBB0_631
	s_cmp_eq_u32 s40, 0
	s_cselect_b64 s[30:31], -1, 0
	s_cmp_lg_u32 s40, 0
	s_mov_b64 s[38:39], -1
	s_cbranch_scc0 .LBB0_634
	s_lshl_b32 s22, s80, 8
	s_or_b32 s22, s22, s53
	s_ashr_i32 s22, s22, 6
	s_mov_b64 s[38:39], 0
